# mixer-A epilogue: last butterfly step via v_permlane16_swap, no LDS round trips left in the row reductions
# speedup vs baseline: 1.0124x; 1.0014x over previous
.LBB0_405:
	s_or_b64 exec, exec, s[4:5]
	s_waitcnt lgkmcnt(0)
	v_lshlrev_b32_e32 v129, 2, v134
	global_load_dword v132, v129, s[0:1]
	global_load_dword v131, v129, s[0:1] offset:128
	global_load_dword v130, v129, s[0:1] offset:256
	s_nop 0
	global_load_dword v129, v129, s[0:1] offset:384
	v_ashrrev_i32_e32 v135, 3, v128
	v_and_b32_e32 v139, -4, v135
	v_mov_b32_e32 v133, v200
	v_lshl_add_u32 v143, v134, 1, s48
	v_lshl_add_u32 v134, v139, 2, s59
	ds_read_b96 v[136:138], v134
	ds_read_b96 v[140:142], v134 offset:128
	v_sub_f32_e32 v133, 1.0, v133
	s_add_i32 s6, s6, 1
	s_cmp_eq_u32 s6, 4
	s_waitcnt lgkmcnt(0)
	v_mul_f32_e32 v16, v16, v140
	v_mul_f32_e32 v0, v0, v140
	v_fma_f32 v16, v80, v136, -v16
	v_fma_f32 v0, v64, v136, -v0
	v_mul_f32_e32 v64, v16, v16
	v_mul_f32_e32 v32, v32, v140
	v_fmac_f32_e32 v64, v0, v0
	v_fma_f32 v80, v96, v136, -v32
	v_mul_f32_e32 v32, v48, v140
	v_fmac_f32_e32 v64, v80, v80
	v_fma_f32 v48, v112, v136, -v32
	v_fmac_f32_e32 v64, v48, v48
	s_nop 1
	v_add_f32_dpp v32, v64, v64 quad_perm:[1,0,3,2] row_mask:0xf bank_mask:0xf
	s_nop 1
	v_add_f32_dpp v32, v32, v32 quad_perm:[2,3,0,1] row_mask:0xf bank_mask:0xf
	s_nop 1
	v_add_f32_dpp v32, v32, v32 row_half_mirror row_mask:0xf bank_mask:0xf
	s_nop 1
	v_add_f32_dpp v32, v32, v32 row_mirror row_mask:0xf bank_mask:0xf
	v_mov_b32_e32 v64, v32
	s_nop 1
	v_permlane16_swap_b32_e32 v32, v64
	v_add_f32_e32 v32, v32, v64
	v_fmamk_f32 v32, v32, 0x3c000000, v204
	v_rsq_f32_e32 v32, v32
	s_nop 0
	v_mul_f32_e32 v64, v133, v32
	v_mul_f32_e32 v0, v0, v64
	v_mul_f32_e32 v16, v16, v64
	v_lshl_add_u32 v32, v139, 8, v143
	v_mul_f32_e32 v80, v80, v64
	v_mul_f32_e32 v48, v48, v64
	s_waitcnt vmcnt(3)
	v_mul_f32_e32 v0, v132, v0
	s_waitcnt vmcnt(2)
	v_mul_f32_e32 v16, v131, v16
	v_cvt_pk_bf16_f32 v0, v0, s0
	s_waitcnt vmcnt(1)
	v_mul_f32_e32 v80, v130, v80
	ds_write_b16 v32, v0
	v_cvt_pk_bf16_f32 v0, v16, s0
	s_waitcnt vmcnt(0)
	v_mul_f32_e32 v48, v129, v48
	ds_write_b16 v32, v0 offset:64
	v_cvt_pk_bf16_f32 v0, v80, s0
	ds_write_b16 v32, v0 offset:128
	v_cvt_pk_bf16_f32 v0, v48, s0
	ds_write_b16 v32, v0 offset:192
	v_mul_f32_e32 v0, v1, v141
	v_mul_f32_e32 v1, v17, v141
	v_fma_f32 v1, v81, v137, -v1
	v_fma_f32 v0, v65, v137, -v0
	v_mul_f32_e32 v16, v1, v1
	v_mul_f32_e32 v17, v33, v141
	v_fmac_f32_e32 v16, v0, v0
	v_fma_f32 v17, v97, v137, -v17
	v_mul_f32_e32 v33, v49, v141
	v_fmac_f32_e32 v16, v17, v17
	v_fma_f32 v33, v113, v137, -v33
	v_fmac_f32_e32 v16, v33, v33
	s_nop 1
	v_add_f32_dpp v16, v16, v16 quad_perm:[1,0,3,2] row_mask:0xf bank_mask:0xf
	s_nop 1
	v_add_f32_dpp v16, v16, v16 quad_perm:[2,3,0,1] row_mask:0xf bank_mask:0xf
	s_nop 1
	v_add_f32_dpp v16, v16, v16 row_half_mirror row_mask:0xf bank_mask:0xf
	s_nop 1
	v_add_f32_dpp v16, v16, v16 row_mirror row_mask:0xf bank_mask:0xf
	v_mov_b32_e32 v48, v16
	s_nop 1
	v_permlane16_swap_b32_e32 v16, v48
	v_add_f32_e32 v16, v16, v48
	v_fmamk_f32 v16, v16, 0x3c000000, v204
	v_rsq_f32_e32 v16, v16
	s_nop 0
	v_mul_f32_e32 v16, v133, v16
	v_mul_f32_e32 v0, v0, v16
	v_mul_f32_e32 v0, v132, v0
	v_mul_f32_e32 v1, v1, v16
	v_mul_f32_e32 v1, v131, v1
	v_mul_f32_e32 v17, v17, v16
	v_cvt_pk_bf16_f32 v0, v0, s0
	v_mul_f32_e32 v17, v130, v17
	v_mul_f32_e32 v16, v33, v16
	ds_write_b16 v32, v0 offset:256
	v_cvt_pk_bf16_f32 v0, v1, s0
	v_mul_f32_e32 v16, v129, v16
	ds_write_b16 v32, v0 offset:320
	v_cvt_pk_bf16_f32 v0, v17, s0
	ds_write_b16 v32, v0 offset:384
	v_cvt_pk_bf16_f32 v0, v16, s0
	v_mul_f32_e32 v1, v18, v142
	ds_write_b16 v32, v0 offset:448
	v_mul_f32_e32 v0, v2, v142
	v_fma_f32 v1, v82, v138, -v1
	v_fma_f32 v0, v66, v138, -v0
	v_mul_f32_e32 v2, v1, v1
	v_mul_f32_e32 v16, v34, v142
	v_fmac_f32_e32 v2, v0, v0
	v_fma_f32 v16, v98, v138, -v16
	v_mul_f32_e32 v17, v50, v142
	v_fmac_f32_e32 v2, v16, v16
	v_fma_f32 v17, v114, v138, -v17
	v_fmac_f32_e32 v2, v17, v17
	s_nop 1
	v_add_f32_dpp v2, v2, v2 quad_perm:[1,0,3,2] row_mask:0xf bank_mask:0xf
	s_nop 1
	v_add_f32_dpp v2, v2, v2 quad_perm:[2,3,0,1] row_mask:0xf bank_mask:0xf
	s_nop 1
	v_add_f32_dpp v2, v2, v2 row_half_mirror row_mask:0xf bank_mask:0xf
	s_nop 1
	v_add_f32_dpp v2, v2, v2 row_mirror row_mask:0xf bank_mask:0xf
	v_mov_b32_e32 v18, v2
	s_nop 1
	v_permlane16_swap_b32_e32 v2, v18
	v_add_f32_e32 v2, v2, v18
	v_fmamk_f32 v2, v2, 0x3c000000, v204
	v_rsq_f32_e32 v2, v2
	s_nop 0
	v_mul_f32_e32 v2, v133, v2
	v_mul_f32_e32 v0, v0, v2
	v_mul_f32_e32 v0, v132, v0
	v_mul_f32_e32 v1, v1, v2
	v_mul_f32_e32 v1, v131, v1
	v_mul_f32_e32 v16, v16, v2
	v_cvt_pk_bf16_f32 v0, v0, s0
	v_mul_f32_e32 v16, v130, v16
	v_mul_f32_e32 v2, v17, v2
	ds_write_b16 v32, v0 offset:512
	v_cvt_pk_bf16_f32 v0, v1, s0
	v_mul_f32_e32 v2, v129, v2
	ds_write_b16 v32, v0 offset:576
	v_cvt_pk_bf16_f32 v0, v16, s0
	ds_write_b16 v32, v0 offset:640
	v_cvt_pk_bf16_f32 v0, v2, s0
	v_or_b32_e32 v2, 3, v135
	ds_write_b16 v32, v0 offset:704
	v_lshl_add_u32 v0, v2, 2, s59
	ds_read2_b32 v[0:1], v0 offset1:32
	v_lshl_add_u32 v2, v2, 8, v143
	s_waitcnt lgkmcnt(0)
	v_mul_f32_e32 v16, v19, v1
	v_mul_f32_e32 v3, v3, v1
	v_fma_f32 v16, v83, v0, -v16
	v_fma_f32 v3, v67, v0, -v3
	v_mul_f32_e32 v17, v16, v16
	v_mul_f32_e32 v18, v35, v1
	v_fmac_f32_e32 v17, v3, v3
	v_fma_f32 v18, v99, v0, -v18
	v_mul_f32_e32 v1, v51, v1
	v_fmac_f32_e32 v17, v18, v18
	v_fma_f32 v0, v115, v0, -v1
	v_fmac_f32_e32 v17, v0, v0
	s_nop 1
	v_add_f32_dpp v1, v17, v17 quad_perm:[1,0,3,2] row_mask:0xf bank_mask:0xf
	s_nop 1
	v_add_f32_dpp v1, v1, v1 quad_perm:[2,3,0,1] row_mask:0xf bank_mask:0xf
	s_nop 1
	v_add_f32_dpp v1, v1, v1 row_half_mirror row_mask:0xf bank_mask:0xf
	s_nop 1
	v_add_f32_dpp v1, v1, v1 row_mirror row_mask:0xf bank_mask:0xf
	v_mov_b32_e32 v17, v1
	s_nop 1
	v_permlane16_swap_b32_e32 v1, v17
	v_add_f32_e32 v1, v1, v17
	v_fmamk_f32 v1, v1, 0x3c000000, v204
	v_rsq_f32_e32 v1, v1
	s_nop 0
	v_mul_f32_e32 v1, v133, v1
	v_mul_f32_e32 v3, v3, v1
	v_mul_f32_e32 v3, v132, v3
	v_mul_f32_e32 v16, v16, v1
	v_mul_f32_e32 v16, v131, v16
	v_mul_f32_e32 v17, v18, v1
	v_mul_f32_e32 v0, v0, v1
	v_cvt_pk_bf16_f32 v1, v3, s0
	v_mul_f32_e32 v17, v130, v17
	v_mul_f32_e32 v0, v129, v0
	ds_write_b16 v2, v1
	v_cvt_pk_bf16_f32 v1, v16, s0
	ds_write_b16 v2, v1 offset:64
	v_cvt_pk_bf16_f32 v1, v17, s0
	v_cvt_pk_bf16_f32 v0, v0, s0
	ds_write_b16 v2, v1 offset:128
	ds_write_b16 v2, v0 offset:192
	ds_read_b128 v[0:3], v134 offset:32
	ds_read_b128 v[16:19], v134 offset:160
	s_waitcnt lgkmcnt(0)
	v_mul_f32_e32 v20, v20, v16
	v_mul_f32_e32 v4, v4, v16
	v_fma_f32 v20, v84, v0, -v20
	v_fma_f32 v4, v68, v0, -v4
	v_mul_f32_e32 v33, v20, v20
	v_mul_f32_e32 v34, v36, v16
	v_fmac_f32_e32 v33, v4, v4
	v_fma_f32 v34, v100, v0, -v34
	v_mul_f32_e32 v16, v52, v16
	v_fmac_f32_e32 v33, v34, v34
	v_fma_f32 v0, v116, v0, -v16
	v_fmac_f32_e32 v33, v0, v0
	s_nop 1
	v_add_f32_dpp v16, v33, v33 quad_perm:[1,0,3,2] row_mask:0xf bank_mask:0xf
	s_nop 1
	v_add_f32_dpp v16, v16, v16 quad_perm:[2,3,0,1] row_mask:0xf bank_mask:0xf
	s_nop 1
	v_add_f32_dpp v16, v16, v16 row_half_mirror row_mask:0xf bank_mask:0xf
	s_nop 1
	v_add_f32_dpp v16, v16, v16 row_mirror row_mask:0xf bank_mask:0xf
	v_mov_b32_e32 v33, v16
	s_nop 1
	v_permlane16_swap_b32_e32 v16, v33
	v_add_f32_e32 v16, v16, v33
	v_fmamk_f32 v16, v16, 0x3c000000, v204
	v_rsq_f32_e32 v16, v16
	s_nop 0
	v_mul_f32_e32 v16, v133, v16
	v_mul_f32_e32 v4, v4, v16
	v_mul_f32_e32 v4, v132, v4
	v_mul_f32_e32 v20, v20, v16
	v_mul_f32_e32 v20, v131, v20
	v_mul_f32_e32 v33, v34, v16
	v_cvt_pk_bf16_f32 v4, v4, s0
	v_mul_f32_e32 v33, v130, v33
	v_mul_f32_e32 v0, v0, v16
	ds_write_b16 v32, v4 offset:2048
	v_cvt_pk_bf16_f32 v4, v20, s0
	v_mul_f32_e32 v0, v129, v0
	ds_write_b16 v32, v4 offset:2112
	v_cvt_pk_bf16_f32 v4, v33, s0
	ds_write_b16 v32, v4 offset:2176
	v_cvt_pk_bf16_f32 v0, v0, s0
	v_mul_f32_e32 v4, v21, v17
	ds_write_b16 v32, v0 offset:2240
	v_mul_f32_e32 v0, v5, v17
	v_fma_f32 v4, v85, v1, -v4
	v_fma_f32 v0, v69, v1, -v0
	v_mul_f32_e32 v5, v4, v4
	v_mul_f32_e32 v16, v37, v17
	v_fmac_f32_e32 v5, v0, v0
	v_fma_f32 v16, v101, v1, -v16
	v_mul_f32_e32 v17, v53, v17
	v_fmac_f32_e32 v5, v16, v16
	v_fma_f32 v1, v117, v1, -v17
	v_fmac_f32_e32 v5, v1, v1
	s_nop 1
	v_add_f32_dpp v5, v5, v5 quad_perm:[1,0,3,2] row_mask:0xf bank_mask:0xf
	s_nop 1
	v_add_f32_dpp v5, v5, v5 quad_perm:[2,3,0,1] row_mask:0xf bank_mask:0xf
	s_nop 1
	v_add_f32_dpp v5, v5, v5 row_half_mirror row_mask:0xf bank_mask:0xf
	s_nop 1
	v_add_f32_dpp v5, v5, v5 row_mirror row_mask:0xf bank_mask:0xf
	v_mov_b32_e32 v17, v5
	s_nop 1
	v_permlane16_swap_b32_e32 v5, v17
	v_add_f32_e32 v5, v5, v17
	v_fmamk_f32 v5, v5, 0x3c000000, v204
	v_rsq_f32_e32 v5, v5
	s_nop 0
	v_mul_f32_e32 v5, v133, v5
	v_mul_f32_e32 v0, v0, v5
	v_mul_f32_e32 v0, v132, v0
	v_mul_f32_e32 v4, v4, v5
	v_mul_f32_e32 v4, v131, v4
	v_mul_f32_e32 v16, v16, v5
	v_cvt_pk_bf16_f32 v0, v0, s0
	v_mul_f32_e32 v16, v130, v16
	v_mul_f32_e32 v1, v1, v5
	ds_write_b16 v32, v0 offset:2304
	v_cvt_pk_bf16_f32 v0, v4, s0
	v_mul_f32_e32 v1, v129, v1
	ds_write_b16 v32, v0 offset:2368
	v_cvt_pk_bf16_f32 v0, v16, s0
	ds_write_b16 v32, v0 offset:2432
	v_cvt_pk_bf16_f32 v0, v1, s0
	v_mul_f32_e32 v1, v22, v18
	ds_write_b16 v32, v0 offset:2496
	v_mul_f32_e32 v0, v6, v18
	v_fma_f32 v1, v86, v2, -v1
	v_fma_f32 v0, v70, v2, -v0
	v_mul_f32_e32 v4, v1, v1
	v_mul_f32_e32 v5, v38, v18
	v_fmac_f32_e32 v4, v0, v0
	v_fma_f32 v5, v102, v2, -v5
	v_mul_f32_e32 v6, v54, v18
	v_fmac_f32_e32 v4, v5, v5
	v_fma_f32 v2, v118, v2, -v6
	v_fmac_f32_e32 v4, v2, v2
	s_nop 1
	v_add_f32_dpp v4, v4, v4 quad_perm:[1,0,3,2] row_mask:0xf bank_mask:0xf
	s_nop 1
	v_add_f32_dpp v4, v4, v4 quad_perm:[2,3,0,1] row_mask:0xf bank_mask:0xf
	s_nop 1
	v_add_f32_dpp v4, v4, v4 row_half_mirror row_mask:0xf bank_mask:0xf
	s_nop 1
	v_add_f32_dpp v4, v4, v4 row_mirror row_mask:0xf bank_mask:0xf
	v_mov_b32_e32 v6, v4
	s_nop 1
	v_permlane16_swap_b32_e32 v4, v6
	v_add_f32_e32 v4, v4, v6
	v_fmamk_f32 v4, v4, 0x3c000000, v204
	v_rsq_f32_e32 v4, v4
	s_nop 0
	v_mul_f32_e32 v4, v133, v4
	v_mul_f32_e32 v0, v0, v4
	v_mul_f32_e32 v0, v132, v0
	v_mul_f32_e32 v1, v1, v4
	v_mul_f32_e32 v1, v131, v1
	v_mul_f32_e32 v5, v5, v4
	v_cvt_pk_bf16_f32 v0, v0, s0
	v_mul_f32_e32 v5, v130, v5
	v_mul_f32_e32 v2, v2, v4
	ds_write_b16 v32, v0 offset:2560
	v_cvt_pk_bf16_f32 v0, v1, s0
	v_mul_f32_e32 v2, v129, v2
	ds_write_b16 v32, v0 offset:2624
	v_cvt_pk_bf16_f32 v0, v5, s0
	ds_write_b16 v32, v0 offset:2688
	v_cvt_pk_bf16_f32 v0, v2, s0
	v_mul_f32_e32 v1, v23, v19
	ds_write_b16 v32, v0 offset:2752
	v_mul_f32_e32 v0, v7, v19
	v_fma_f32 v1, v87, v3, -v1
	v_fma_f32 v0, v71, v3, -v0
	v_mul_f32_e32 v2, v1, v1
	v_mul_f32_e32 v4, v39, v19
	v_fmac_f32_e32 v2, v0, v0
	v_fma_f32 v4, v103, v3, -v4
	v_mul_f32_e32 v5, v55, v19
	v_fmac_f32_e32 v2, v4, v4
	v_fma_f32 v3, v119, v3, -v5
	v_fmac_f32_e32 v2, v3, v3
	s_nop 1
	v_add_f32_dpp v2, v2, v2 quad_perm:[1,0,3,2] row_mask:0xf bank_mask:0xf
	s_nop 1
	v_add_f32_dpp v2, v2, v2 quad_perm:[2,3,0,1] row_mask:0xf bank_mask:0xf
	s_nop 1
	v_add_f32_dpp v2, v2, v2 row_half_mirror row_mask:0xf bank_mask:0xf
	s_nop 1
	v_add_f32_dpp v2, v2, v2 row_mirror row_mask:0xf bank_mask:0xf
	v_mov_b32_e32 v5, v2
	s_nop 1
	v_permlane16_swap_b32_e32 v2, v5
	v_add_f32_e32 v2, v2, v5
	v_fmamk_f32 v2, v2, 0x3c000000, v204
	v_rsq_f32_e32 v2, v2
	s_nop 0
	v_mul_f32_e32 v2, v133, v2
	v_mul_f32_e32 v0, v0, v2
	v_mul_f32_e32 v0, v132, v0
	v_mul_f32_e32 v1, v1, v2
	v_mul_f32_e32 v1, v131, v1
	v_mul_f32_e32 v4, v4, v2
	v_cvt_pk_bf16_f32 v0, v0, s0
	v_mul_f32_e32 v4, v130, v4
	v_mul_f32_e32 v2, v3, v2
	ds_write_b16 v32, v0 offset:2816
	v_cvt_pk_bf16_f32 v0, v1, s0
	v_mul_f32_e32 v2, v129, v2
	ds_write_b16 v32, v0 offset:2880
	v_cvt_pk_bf16_f32 v0, v4, s0
	ds_write_b16 v32, v0 offset:2944
	v_cvt_pk_bf16_f32 v0, v2, s0
	ds_write_b16 v32, v0 offset:3008
	ds_read_b128 v[0:3], v134 offset:64
	ds_read_b128 v[4:7], v134 offset:192
	s_waitcnt lgkmcnt(0)
	v_mul_f32_e32 v16, v24, v4
	v_mul_f32_e32 v8, v8, v4
	v_fma_f32 v16, v88, v0, -v16
	v_fma_f32 v8, v72, v0, -v8
	v_mul_f32_e32 v17, v16, v16
	v_mul_f32_e32 v18, v40, v4
	v_fmac_f32_e32 v17, v8, v8
	v_fma_f32 v18, v104, v0, -v18
	v_mul_f32_e32 v4, v56, v4
	v_fmac_f32_e32 v17, v18, v18
	v_fma_f32 v0, v120, v0, -v4
	v_fmac_f32_e32 v17, v0, v0
	s_nop 1
	v_add_f32_dpp v4, v17, v17 quad_perm:[1,0,3,2] row_mask:0xf bank_mask:0xf
	s_nop 1
	v_add_f32_dpp v4, v4, v4 quad_perm:[2,3,0,1] row_mask:0xf bank_mask:0xf
	s_nop 1
	v_add_f32_dpp v4, v4, v4 row_half_mirror row_mask:0xf bank_mask:0xf
	s_nop 1
	v_add_f32_dpp v4, v4, v4 row_mirror row_mask:0xf bank_mask:0xf
	v_mov_b32_e32 v17, v4
	s_nop 1
	v_permlane16_swap_b32_e32 v4, v17
	v_add_f32_e32 v4, v4, v17
	v_fmamk_f32 v4, v4, 0x3c000000, v204
	v_rsq_f32_e32 v4, v4
	s_nop 0
	v_mul_f32_e32 v4, v133, v4
	v_mul_f32_e32 v8, v8, v4
	v_mul_f32_e32 v8, v132, v8
	v_mul_f32_e32 v16, v16, v4
	v_mul_f32_e32 v16, v131, v16
	v_mul_f32_e32 v17, v18, v4
	v_mul_f32_e32 v0, v0, v4
	v_cvt_pk_bf16_f32 v4, v8, s0
	v_mul_f32_e32 v17, v130, v17
	ds_write_b16 v32, v4 offset:4096
	v_cvt_pk_bf16_f32 v4, v16, s0
	v_mul_f32_e32 v0, v129, v0
	ds_write_b16 v32, v4 offset:4160
	v_cvt_pk_bf16_f32 v4, v17, s0
	ds_write_b16 v32, v4 offset:4224
	v_cvt_pk_bf16_f32 v0, v0, s0
	v_mul_f32_e32 v4, v25, v5
	ds_write_b16 v32, v0 offset:4288
	v_mul_f32_e32 v0, v9, v5
	v_fma_f32 v4, v89, v1, -v4
	v_fma_f32 v0, v73, v1, -v0
	v_mul_f32_e32 v8, v4, v4
	v_mul_f32_e32 v9, v41, v5
	v_fmac_f32_e32 v8, v0, v0
	v_fma_f32 v9, v105, v1, -v9
	v_mul_f32_e32 v5, v57, v5
	v_fmac_f32_e32 v8, v9, v9
	v_fma_f32 v1, v121, v1, -v5
	v_fmac_f32_e32 v8, v1, v1
	s_nop 1
	v_add_f32_dpp v5, v8, v8 quad_perm:[1,0,3,2] row_mask:0xf bank_mask:0xf
	s_nop 1
	v_add_f32_dpp v5, v5, v5 quad_perm:[2,3,0,1] row_mask:0xf bank_mask:0xf
	s_nop 1
	v_add_f32_dpp v5, v5, v5 row_half_mirror row_mask:0xf bank_mask:0xf
	s_nop 1
	v_add_f32_dpp v5, v5, v5 row_mirror row_mask:0xf bank_mask:0xf
	v_mov_b32_e32 v8, v5
	s_nop 1
	v_permlane16_swap_b32_e32 v5, v8
	v_add_f32_e32 v5, v5, v8
	v_fmamk_f32 v5, v5, 0x3c000000, v204
	v_rsq_f32_e32 v5, v5
	s_nop 0
	v_mul_f32_e32 v5, v133, v5
	v_mul_f32_e32 v0, v0, v5
	v_mul_f32_e32 v0, v132, v0
	v_mul_f32_e32 v4, v4, v5
	v_mul_f32_e32 v4, v131, v4
	v_mul_f32_e32 v8, v9, v5
	v_cvt_pk_bf16_f32 v0, v0, s0
	v_mul_f32_e32 v8, v130, v8
	v_mul_f32_e32 v1, v1, v5
	ds_write_b16 v32, v0 offset:4352
	v_cvt_pk_bf16_f32 v0, v4, s0
	v_mul_f32_e32 v1, v129, v1
	ds_write_b16 v32, v0 offset:4416
	v_cvt_pk_bf16_f32 v0, v8, s0
	ds_write_b16 v32, v0 offset:4480
	v_cvt_pk_bf16_f32 v0, v1, s0
	v_mul_f32_e32 v1, v26, v6
	ds_write_b16 v32, v0 offset:4544
	v_mul_f32_e32 v0, v10, v6
	v_fma_f32 v1, v90, v2, -v1
	v_fma_f32 v0, v74, v2, -v0
	v_mul_f32_e32 v4, v1, v1
	v_mul_f32_e32 v5, v42, v6
	v_fmac_f32_e32 v4, v0, v0
	v_fma_f32 v5, v106, v2, -v5
	v_mul_f32_e32 v6, v58, v6
	v_fmac_f32_e32 v4, v5, v5
	v_fma_f32 v2, v122, v2, -v6
	v_fmac_f32_e32 v4, v2, v2
	s_nop 1
	v_add_f32_dpp v4, v4, v4 quad_perm:[1,0,3,2] row_mask:0xf bank_mask:0xf
	s_nop 1
	v_add_f32_dpp v4, v4, v4 quad_perm:[2,3,0,1] row_mask:0xf bank_mask:0xf
	s_nop 1
	v_add_f32_dpp v4, v4, v4 row_half_mirror row_mask:0xf bank_mask:0xf
	s_nop 1
	v_add_f32_dpp v4, v4, v4 row_mirror row_mask:0xf bank_mask:0xf
	v_mov_b32_e32 v6, v4
	s_nop 1
	v_permlane16_swap_b32_e32 v4, v6
	v_add_f32_e32 v4, v4, v6
	v_fmamk_f32 v4, v4, 0x3c000000, v204
	v_rsq_f32_e32 v4, v4
	s_nop 0
	v_mul_f32_e32 v4, v133, v4
	v_mul_f32_e32 v0, v0, v4
	v_mul_f32_e32 v0, v132, v0
	v_mul_f32_e32 v1, v1, v4
	v_mul_f32_e32 v1, v131, v1
	v_mul_f32_e32 v5, v5, v4
	v_cvt_pk_bf16_f32 v0, v0, s0
	v_mul_f32_e32 v5, v130, v5
	v_mul_f32_e32 v2, v2, v4
	ds_write_b16 v32, v0 offset:4608
	v_cvt_pk_bf16_f32 v0, v1, s0
	v_mul_f32_e32 v2, v129, v2
	ds_write_b16 v32, v0 offset:4672
	v_cvt_pk_bf16_f32 v0, v5, s0
	ds_write_b16 v32, v0 offset:4736
	v_cvt_pk_bf16_f32 v0, v2, s0
	v_mul_f32_e32 v1, v27, v7
	ds_write_b16 v32, v0 offset:4800
	v_mul_f32_e32 v0, v11, v7
	v_fma_f32 v1, v91, v3, -v1
	v_fma_f32 v0, v75, v3, -v0
	v_mul_f32_e32 v2, v1, v1
	v_mul_f32_e32 v4, v43, v7
	v_fmac_f32_e32 v2, v0, v0
	v_fma_f32 v4, v107, v3, -v4
	v_mul_f32_e32 v5, v59, v7
	v_fmac_f32_e32 v2, v4, v4
	v_fma_f32 v3, v123, v3, -v5
	v_fmac_f32_e32 v2, v3, v3
	s_nop 1
	v_add_f32_dpp v2, v2, v2 quad_perm:[1,0,3,2] row_mask:0xf bank_mask:0xf
	s_nop 1
	v_add_f32_dpp v2, v2, v2 quad_perm:[2,3,0,1] row_mask:0xf bank_mask:0xf
	s_nop 1
	v_add_f32_dpp v2, v2, v2 row_half_mirror row_mask:0xf bank_mask:0xf
	s_nop 1
	v_add_f32_dpp v2, v2, v2 row_mirror row_mask:0xf bank_mask:0xf
	v_mov_b32_e32 v5, v2
	s_nop 1
	v_permlane16_swap_b32_e32 v2, v5
	v_add_f32_e32 v2, v2, v5
	v_fmamk_f32 v2, v2, 0x3c000000, v204
	v_rsq_f32_e32 v2, v2
	s_nop 0
	v_mul_f32_e32 v2, v133, v2
	v_mul_f32_e32 v0, v0, v2
	v_mul_f32_e32 v0, v132, v0
	v_mul_f32_e32 v1, v1, v2
	v_mul_f32_e32 v1, v131, v1
	v_mul_f32_e32 v4, v4, v2
	v_cvt_pk_bf16_f32 v0, v0, s0
	v_mul_f32_e32 v4, v130, v4
	v_mul_f32_e32 v2, v3, v2
	ds_write_b16 v32, v0 offset:4864
	v_cvt_pk_bf16_f32 v0, v1, s0
	v_mul_f32_e32 v2, v129, v2
	ds_write_b16 v32, v0 offset:4928
	v_cvt_pk_bf16_f32 v0, v4, s0
	ds_write_b16 v32, v0 offset:4992
	v_cvt_pk_bf16_f32 v0, v2, s0
	ds_write_b16 v32, v0 offset:5056
	ds_read_b128 v[0:3], v134 offset:96
	ds_read_b128 v[4:7], v134 offset:224
	s_waitcnt lgkmcnt(0)
	v_mul_f32_e32 v9, v28, v4
	v_mul_f32_e32 v8, v12, v4
	v_fma_f32 v9, v92, v0, -v9
	v_fma_f32 v8, v76, v0, -v8
	v_mul_f32_e32 v10, v9, v9
	v_mul_f32_e32 v11, v44, v4
	v_fmac_f32_e32 v10, v8, v8
	v_fma_f32 v11, v108, v0, -v11
	v_mul_f32_e32 v4, v60, v4
	v_fmac_f32_e32 v10, v11, v11
	v_fma_f32 v0, v124, v0, -v4
	v_fmac_f32_e32 v10, v0, v0
	s_nop 1
	v_add_f32_dpp v4, v10, v10 quad_perm:[1,0,3,2] row_mask:0xf bank_mask:0xf
	s_nop 1
	v_add_f32_dpp v4, v4, v4 quad_perm:[2,3,0,1] row_mask:0xf bank_mask:0xf
	s_nop 1
	v_add_f32_dpp v4, v4, v4 row_half_mirror row_mask:0xf bank_mask:0xf
	s_nop 1
	v_add_f32_dpp v4, v4, v4 row_mirror row_mask:0xf bank_mask:0xf
	v_mov_b32_e32 v10, v4
	s_nop 1
	v_permlane16_swap_b32_e32 v4, v10
	v_add_f32_e32 v4, v4, v10
	v_fmamk_f32 v4, v4, 0x3c000000, v204
	v_rsq_f32_e32 v4, v4
	s_nop 0
	v_mul_f32_e32 v4, v133, v4
	v_mul_f32_e32 v8, v8, v4
	v_mul_f32_e32 v8, v132, v8
	v_mul_f32_e32 v9, v9, v4
	v_mul_f32_e32 v9, v131, v9
	v_mul_f32_e32 v10, v11, v4
	v_mul_f32_e32 v0, v0, v4
	v_cvt_pk_bf16_f32 v4, v8, s0
	v_mul_f32_e32 v10, v130, v10
	ds_write_b16 v32, v4 offset:6144
	v_cvt_pk_bf16_f32 v4, v9, s0
	v_mul_f32_e32 v0, v129, v0
	ds_write_b16 v32, v4 offset:6208
	v_cvt_pk_bf16_f32 v4, v10, s0
	ds_write_b16 v32, v4 offset:6272
	v_cvt_pk_bf16_f32 v0, v0, s0
	v_mul_f32_e32 v4, v29, v5
	ds_write_b16 v32, v0 offset:6336
	v_mul_f32_e32 v0, v13, v5
	v_fma_f32 v4, v93, v1, -v4
	v_fma_f32 v0, v77, v1, -v0
	v_mul_f32_e32 v8, v4, v4
	v_mul_f32_e32 v9, v45, v5
	v_fmac_f32_e32 v8, v0, v0
	v_fma_f32 v9, v109, v1, -v9
	v_mul_f32_e32 v5, v61, v5
	v_fmac_f32_e32 v8, v9, v9
	v_fma_f32 v1, v125, v1, -v5
	v_fmac_f32_e32 v8, v1, v1
	s_nop 1
	v_add_f32_dpp v5, v8, v8 quad_perm:[1,0,3,2] row_mask:0xf bank_mask:0xf
	s_nop 1
	v_add_f32_dpp v5, v5, v5 quad_perm:[2,3,0,1] row_mask:0xf bank_mask:0xf
	s_nop 1
	v_add_f32_dpp v5, v5, v5 row_half_mirror row_mask:0xf bank_mask:0xf
	s_nop 1
	v_add_f32_dpp v5, v5, v5 row_mirror row_mask:0xf bank_mask:0xf
	v_mov_b32_e32 v8, v5
	s_nop 1
	v_permlane16_swap_b32_e32 v5, v8
	v_add_f32_e32 v5, v5, v8
	v_fmamk_f32 v5, v5, 0x3c000000, v204
	v_rsq_f32_e32 v5, v5
	s_nop 0
	v_mul_f32_e32 v5, v133, v5
	v_mul_f32_e32 v0, v0, v5
	v_mul_f32_e32 v0, v132, v0
	v_mul_f32_e32 v4, v4, v5
	v_mul_f32_e32 v4, v131, v4
	v_mul_f32_e32 v8, v9, v5
	v_cvt_pk_bf16_f32 v0, v0, s0
	v_mul_f32_e32 v8, v130, v8
	v_mul_f32_e32 v1, v1, v5
	ds_write_b16 v32, v0 offset:6400
	v_cvt_pk_bf16_f32 v0, v4, s0
	v_mul_f32_e32 v1, v129, v1
	ds_write_b16 v32, v0 offset:6464
	v_cvt_pk_bf16_f32 v0, v8, s0
	ds_write_b16 v32, v0 offset:6528
	v_cvt_pk_bf16_f32 v0, v1, s0
	v_mul_f32_e32 v1, v30, v6
	ds_write_b16 v32, v0 offset:6592
	v_mul_f32_e32 v0, v14, v6
	v_fma_f32 v1, v94, v2, -v1
	v_fma_f32 v0, v78, v2, -v0
	v_mul_f32_e32 v4, v1, v1
	v_mul_f32_e32 v5, v46, v6
	v_fmac_f32_e32 v4, v0, v0
	v_fma_f32 v5, v110, v2, -v5
	v_mul_f32_e32 v6, v62, v6
	v_fmac_f32_e32 v4, v5, v5
	v_fma_f32 v2, v126, v2, -v6
	v_fmac_f32_e32 v4, v2, v2
	s_nop 1
	v_add_f32_dpp v4, v4, v4 quad_perm:[1,0,3,2] row_mask:0xf bank_mask:0xf
	s_nop 1
	v_add_f32_dpp v4, v4, v4 quad_perm:[2,3,0,1] row_mask:0xf bank_mask:0xf
	s_nop 1
	v_add_f32_dpp v4, v4, v4 row_half_mirror row_mask:0xf bank_mask:0xf
	s_nop 1
	v_add_f32_dpp v4, v4, v4 row_mirror row_mask:0xf bank_mask:0xf
	v_mov_b32_e32 v6, v4
	s_nop 1
	v_permlane16_swap_b32_e32 v4, v6
	v_add_f32_e32 v4, v4, v6
	v_fmamk_f32 v4, v4, 0x3c000000, v204
	v_rsq_f32_e32 v4, v4
	s_nop 0
	v_mul_f32_e32 v4, v133, v4
	v_mul_f32_e32 v0, v0, v4
	v_mul_f32_e32 v0, v132, v0
	v_mul_f32_e32 v1, v1, v4
	v_mul_f32_e32 v1, v131, v1
	v_mul_f32_e32 v5, v5, v4
	v_cvt_pk_bf16_f32 v0, v0, s0
	v_mul_f32_e32 v5, v130, v5
	v_mul_f32_e32 v2, v2, v4
	ds_write_b16 v32, v0 offset:6656
	v_cvt_pk_bf16_f32 v0, v1, s0
	v_mul_f32_e32 v2, v129, v2
	ds_write_b16 v32, v0 offset:6720
	v_cvt_pk_bf16_f32 v0, v5, s0
	ds_write_b16 v32, v0 offset:6784
	v_cvt_pk_bf16_f32 v0, v2, s0
	v_mul_f32_e32 v1, v31, v7
	ds_write_b16 v32, v0 offset:6848
	v_mul_f32_e32 v0, v15, v7
	v_fma_f32 v1, v95, v3, -v1
	v_fma_f32 v0, v79, v3, -v0
	v_mul_f32_e32 v2, v1, v1
	v_mul_f32_e32 v4, v47, v7
	v_fmac_f32_e32 v2, v0, v0
	v_fma_f32 v4, v111, v3, -v4
	v_mul_f32_e32 v5, v63, v7
	v_fmac_f32_e32 v2, v4, v4
	v_fma_f32 v3, v127, v3, -v5
	v_fmac_f32_e32 v2, v3, v3
	s_nop 1
	v_add_f32_dpp v2, v2, v2 quad_perm:[1,0,3,2] row_mask:0xf bank_mask:0xf
	s_nop 1
	v_add_f32_dpp v2, v2, v2 quad_perm:[2,3,0,1] row_mask:0xf bank_mask:0xf
	s_nop 1
	v_add_f32_dpp v2, v2, v2 row_half_mirror row_mask:0xf bank_mask:0xf
	s_nop 1
	v_add_f32_dpp v2, v2, v2 row_mirror row_mask:0xf bank_mask:0xf
	v_mov_b32_e32 v5, v2
	s_nop 1
	v_permlane16_swap_b32_e32 v2, v5
	v_add_f32_e32 v2, v2, v5
	v_fmamk_f32 v2, v2, 0x3c000000, v204
	v_rsq_f32_e32 v2, v2
	s_nop 0
	v_mul_f32_e32 v2, v133, v2
	v_mul_f32_e32 v0, v0, v2
	v_mul_f32_e32 v0, v132, v0
	v_mul_f32_e32 v1, v1, v2
	v_mul_f32_e32 v1, v131, v1
	v_mul_f32_e32 v4, v4, v2
	v_cvt_pk_bf16_f32 v0, v0, s0
	v_mul_f32_e32 v4, v130, v4
	v_mul_f32_e32 v2, v3, v2
	ds_write_b16 v32, v0 offset:6912
	v_cvt_pk_bf16_f32 v0, v1, s0
	v_mul_f32_e32 v2, v129, v2
	ds_write_b16 v32, v0 offset:6976
	v_cvt_pk_bf16_f32 v0, v4, s0
	ds_write_b16 v32, v0 offset:7040
	v_cvt_pk_bf16_f32 v0, v2, s0
	ds_write_b16 v32, v0 offset:7104
	v_lshlrev_b32_e32 v0, 4, v128
	v_and_b32_e32 v160, 0xf0, v0
	v_add_u32_e32 v6, s48, v160
	v_ashrrev_i32_e32 v4, 4, v128
	s_waitcnt lgkmcnt(0)
	v_lshl_add_u32 v0, v4, 8, v6
	ds_read_b128 v[0:3], v0
	v_ashrrev_i32_e32 v5, 31, v4
	v_lshl_add_u64 v[4:5], s[2:3], 0, v[4:5]
	v_lshlrev_b64 v[4:5], 11, v[4:5]
	v_lshl_add_u64 v[4:5], s[92:93], 0, v[4:5]
	v_lshl_add_u64 v[4:5], v[4:5], 0, v[160:161]
	s_waitcnt lgkmcnt(0)
	global_store_dwordx4 v[4:5], v[0:3], off
	s_nop 1
	v_add_u32_e32 v0, 64, v128
	v_ashrrev_i32_e32 v4, 4, v0
	v_lshl_add_u32 v0, v4, 8, v6
	ds_read_b128 v[0:3], v0
	v_ashrrev_i32_e32 v5, 31, v4
	v_lshl_add_u64 v[4:5], s[2:3], 0, v[4:5]
	v_lshlrev_b64 v[4:5], 11, v[4:5]
	v_lshl_add_u64 v[4:5], s[92:93], 0, v[4:5]
	v_lshl_add_u64 v[4:5], v[4:5], 0, v[160:161]
	s_waitcnt lgkmcnt(0)
	global_store_dwordx4 v[4:5], v[0:3], off
	s_nop 1
	v_add_u32_e32 v0, 0x80, v128
	v_ashrrev_i32_e32 v4, 4, v0
	v_lshl_add_u32 v0, v4, 8, v6
	ds_read_b128 v[0:3], v0
	v_ashrrev_i32_e32 v5, 31, v4
	v_lshl_add_u64 v[4:5], s[2:3], 0, v[4:5]
	v_lshlrev_b64 v[4:5], 11, v[4:5]
	v_lshl_add_u64 v[4:5], s[92:93], 0, v[4:5]
	v_lshl_add_u64 v[4:5], v[4:5], 0, v[160:161]
	s_waitcnt lgkmcnt(0)
	global_store_dwordx4 v[4:5], v[0:3], off
	s_nop 1
	v_add_u32_e32 v0, 0xc0, v128
	v_ashrrev_i32_e32 v4, 4, v0
	v_lshl_add_u32 v0, v4, 8, v6
	ds_read_b128 v[0:3], v0
	v_ashrrev_i32_e32 v5, 31, v4
	v_lshl_add_u64 v[4:5], s[2:3], 0, v[4:5]
	v_lshlrev_b64 v[4:5], 11, v[4:5]
	v_lshl_add_u64 v[4:5], s[92:93], 0, v[4:5]
	v_lshl_add_u64 v[4:5], v[4:5], 0, v[160:161]
	s_waitcnt lgkmcnt(0)
	global_store_dwordx4 v[4:5], v[0:3], off
	s_nop 1
	v_add_u32_e32 v0, 0x100, v128
	v_ashrrev_i32_e32 v4, 4, v0
	v_lshl_add_u32 v0, v4, 8, v6
	ds_read_b128 v[0:3], v0
	v_ashrrev_i32_e32 v5, 31, v4
	v_lshl_add_u64 v[4:5], s[2:3], 0, v[4:5]
	v_lshlrev_b64 v[4:5], 11, v[4:5]
	v_lshl_add_u64 v[4:5], s[92:93], 0, v[4:5]
	v_lshl_add_u64 v[4:5], v[4:5], 0, v[160:161]
	s_waitcnt lgkmcnt(0)
	global_store_dwordx4 v[4:5], v[0:3], off
	s_nop 1
	v_add_u32_e32 v0, 0x140, v128
	v_ashrrev_i32_e32 v4, 4, v0
	v_lshl_add_u32 v0, v4, 8, v6
	ds_read_b128 v[0:3], v0
	v_ashrrev_i32_e32 v5, 31, v4
	v_lshl_add_u64 v[4:5], s[2:3], 0, v[4:5]
	v_lshlrev_b64 v[4:5], 11, v[4:5]
	v_lshl_add_u64 v[4:5], s[92:93], 0, v[4:5]
	v_lshl_add_u64 v[4:5], v[4:5], 0, v[160:161]
	s_waitcnt lgkmcnt(0)
	global_store_dwordx4 v[4:5], v[0:3], off
	s_nop 1
	v_add_u32_e32 v0, 0x180, v128
	v_ashrrev_i32_e32 v4, 4, v0
	v_lshl_add_u32 v0, v4, 8, v6
	ds_read_b128 v[0:3], v0
	v_ashrrev_i32_e32 v5, 31, v4
	v_lshl_add_u64 v[4:5], s[2:3], 0, v[4:5]
	v_lshlrev_b64 v[4:5], 11, v[4:5]
	v_lshl_add_u64 v[4:5], s[92:93], 0, v[4:5]
	v_lshl_add_u64 v[4:5], v[4:5], 0, v[160:161]
	s_waitcnt lgkmcnt(0)
	global_store_dwordx4 v[4:5], v[0:3], off
	s_nop 1
	v_add_u32_e32 v0, 0x1c0, v128
	v_ashrrev_i32_e32 v4, 4, v0
	v_lshl_add_u32 v0, v4, 8, v6
	ds_read_b128 v[0:3], v0
	v_ashrrev_i32_e32 v5, 31, v4
	v_lshl_add_u64 v[4:5], s[2:3], 0, v[4:5]
	v_lshlrev_b64 v[4:5], 11, v[4:5]
	v_lshl_add_u64 v[4:5], s[92:93], 0, v[4:5]
	v_lshl_add_u64 v[4:5], v[4:5], 0, v[160:161]
	s_waitcnt lgkmcnt(0)
	global_store_dwordx4 v[4:5], v[0:3], off
	s_waitcnt vmcnt(0) lgkmcnt(0)
	s_barrier
	s_cbranch_scc1 .LBB0_419
